# v12 plus: static s_setprio 1 for waves 4-7 during attention units; residual (out/down) epilogue issues the first row-half's sum-of-squares atomics after the second half's loads so those loads do not q
# baseline (speedup 1.0000x reference)
.LBB0_198:
	s_or_b64 exec, exec, s[2:3]
	v_mov_b32_e32 v0, s38
	s_waitcnt lgkmcnt(0)
	s_barrier
	ds_read_b32 v156, v0
	s_movk_i32 s2, 0x83
	s_waitcnt lgkmcnt(0)
	s_barrier
	v_cmp_lt_i32_e32 vcc, s2, v156
	s_mov_b64 s[2:3], -1
	s_cbranch_vccnz .LBB0_193
	v_cmp_lt_i32_e32 vcc, 3, v156
	s_cbranch_vccz .LBB0_219
	v_add_u32_e32 v0, -4, v156
	v_mov_b32_e32 v87, v218
	v_not_b32_e32 v1, v0
	v_bfe_u32 v81, v1, 1, 5
	v_readfirstlane_b32 s2, v87
	s_nop 3
	s_cmpk_gt_u32 s2, 0xff
	s_cbranch_scc0 .Lattn_prio_done
	s_setprio 1
.Lattn_prio_done:
	s_bfe_u32 s3, s2, 0x20006
	v_lshrrev_b32_e32 v0, 5, v0
	v_lshlrev_b32_e32 v86, 7, v81
	s_lshl_b32 s28, s3, 5
	v_and_b32_e32 v0, 2, v0
	v_and_b32_e32 v1, 1, v156
	v_or_b32_e32 v152, s28, v86
	v_or_b32_e32 v16, v0, v1
	v_and_b32_e32 v88, 31, v87
	v_or_b32_e32 v0, s46, v152
	v_or_b32_e32 v150, v0, v88
	v_mov_b64_e32 v[0:1], s[24:25]
	v_mad_u64_u32 v[0:1], s[26:27], v150, s10, v[0:1]
	v_lshlrev_b32_e32 v168, 8, v16
	v_lshlrev_b32_e32 v2, 4, v87
	v_lshl_add_u64 v[18:19], v[0:1], 0, v[168:169]
	v_ashrrev_i32_e32 v89, 4, v87
	v_lshl_add_u64 v[0:1], s[8:9], 0, v[168:169]
	v_and_b32_e32 v168, 0xf0, v2
	v_lshl_add_u64 v[20:21], v[0:1], 0, v[168:169]
	v_add_u32_e32 v8, 32, v89
	v_mad_i64_i32 v[4:5], s[26:27], v89, s10, v[20:21]
	v_mad_i64_i32 v[12:13], s[26:27], v8, s10, v[20:21]
	global_load_dwordx4 v[0:3], v[4:5], off offset:1024
	s_nop 0
	global_load_dwordx4 v[4:7], v[4:5], off offset:2048
	s_nop 0
	global_load_dwordx4 v[8:11], v[12:13], off offset:1024
	s_nop 0
	global_load_dwordx4 v[12:15], v[12:13], off offset:2048
	s_ashr_i32 s11, s2, 8
	s_lshl_b32 s26, s11, 6
	v_bfe_u32 v17, v87, 5, 1
	s_ashr_i32 s27, s26, 31
	v_lshl_add_u64 v[18:19], s[26:27], 1, v[18:19]
	v_lshlrev_b32_e32 v22, 4, v17
	v_mov_b32_e32 v23, v169
	v_lshl_add_u64 v[18:19], v[18:19], 0, v[22:23]
	global_load_dwordx4 v[112:115], v[18:19], off
	global_load_dwordx4 v[116:119], v[18:19], off offset:32
	global_load_dwordx4 v[120:123], v[18:19], off offset:64
	global_load_dwordx4 v[124:127], v[18:19], off offset:96
	s_movk_i32 s26, 0x140
	v_mul_lo_u32 v153, v89, s62
	v_mul_lo_u32 v154, v89, s26
	v_add_u32_e32 v158, 0, v168
	v_mul_u32_u24_e32 v23, 0x110, v88
	v_add_u32_e32 v24, 64, v89
	v_add_u32_e32 v26, 0x2800, v154
	v_lshl_or_b32 v22, s11, 7, v22
	v_add_u32_e32 v90, v158, v153
	v_add_u32_e32 v25, 0x60, v89
	v_add3_u32 v157, 0, v23, v22
	v_add_u32_e32 v92, v158, v154
	v_add_u32_e32 v91, v158, v26
	v_lshlrev_b32_e32 v151, 2, v17
	v_lshlrev_b32_e32 v17, 10, v16
	v_add_u32_e32 v17, 0, v17
	v_add_u32_e32 v159, 0x12800, v17
	s_waitcnt vmcnt(7)
	ds_write_b128 v90, v[0:3]
	s_waitcnt vmcnt(6)
	ds_write_b128 v92, v[4:7] offset:34816
	s_waitcnt vmcnt(5)
	ds_write_b128 v90, v[8:11] offset:8704
	s_waitcnt vmcnt(4)
	ds_write_b128 v91, v[12:15] offset:34816
	v_mad_i64_i32 v[4:5], s[26:27], v24, s10, v[20:21]
	s_waitcnt lgkmcnt(0)
	s_barrier
	ds_read_b128 v[0:3], v157
	v_mad_i64_i32 v[6:7], s[26:27], v25, s10, v[20:21]
	global_load_dwordx4 v[128:131], v[4:5], off offset:1024
	global_load_dwordx4 v[132:135], v[4:5], off offset:2048
	global_load_dwordx4 v[136:139], v[6:7], off offset:1024
	global_load_dwordx4 v[140:143], v[6:7], off offset:2048
	ds_read_b128 v[18:21], v157 offset:8704
	s_waitcnt vmcnt(7) lgkmcnt(0)
	v_mfma_f32_32x32x16_bf16 v[64:79], v[18:21], v[112:115], 0
	ds_read_b128 v[18:21], v157 offset:32
	s_movk_i32 s26, 0x99
	v_cmp_lt_u32_e32 vcc, s26, v152
	s_and_b64 vcc, exec, vcc
	v_mfma_f32_32x32x16_bf16 v[0:15], v[0:3], v[112:115], 0
	s_waitcnt vmcnt(6) lgkmcnt(0)
	v_mfma_f32_32x32x16_bf16 v[0:15], v[18:21], v[116:119], v[0:15]
	ds_read_b128 v[18:21], v157 offset:8736
	s_waitcnt lgkmcnt(0)
	v_mfma_f32_32x32x16_bf16 v[64:79], v[18:21], v[116:119], v[64:79]
	ds_read_b128 v[18:21], v157 offset:64
	s_waitcnt vmcnt(5) lgkmcnt(0)
	v_mfma_f32_32x32x16_bf16 v[0:15], v[18:21], v[120:123], v[0:15]
	ds_read_b128 v[18:21], v157 offset:8768
	s_waitcnt lgkmcnt(0)
	v_mfma_f32_32x32x16_bf16 v[64:79], v[18:21], v[120:123], v[64:79]
	ds_read_b128 v[18:21], v157 offset:96
	s_waitcnt vmcnt(4) lgkmcnt(0)
	v_mfma_f32_32x32x16_bf16 v[0:15], v[18:21], v[124:127], v[0:15]
	ds_read_b128 v[18:21], v157 offset:8800
	s_waitcnt lgkmcnt(0)
	v_mfma_f32_32x32x16_bf16 v[64:79], v[18:21], v[124:127], v[64:79]
	s_cbranch_vccnz .LBB0_202
	v_or_b32_e32 v17, 0xc0, v151
	v_or_b32_e32 v18, v152, v88
	v_sub_u32_e32 v17, v17, v18
	v_add_u32_e32 v20, 1, v17
	v_max_i32_e32 v21, 0, v20
	v_max_i32_e32 v20, 0xffffffe0, v20
	v_lshl_add_u32 v22, v20, 2, v159
	v_add_u32_e32 v20, 2, v17
	v_max_i32_e32 v23, 0, v20
	v_max_i32_e32 v20, 0xffffffe0, v20
	v_lshl_add_u32 v24, v20, 2, v159
	v_add_u32_e32 v20, 3, v17
	v_max_i32_e32 v18, 0, v17
	v_max_i32_e32 v19, 0xffffffe0, v17
	v_max_i32_e32 v25, 0, v20
	v_max_i32_e32 v20, 0xffffffe0, v20
	v_lshl_add_u32 v18, v18, 2, v159
	v_lshl_add_u32 v19, v19, 2, v159
	v_lshl_add_u32 v21, v21, 2, v159
	v_lshl_add_u32 v23, v23, 2, v159
	v_lshl_add_u32 v25, v25, 2, v159
	v_lshl_add_u32 v26, v20, 2, v159
	ds_read_b32 v18, v18
	ds_read_b32 v20, v19 offset:128
	ds_read_b32 v19, v21
	ds_read_b32 v21, v22 offset:128
	ds_read_b32 v22, v23
	ds_read_b32 v24, v24 offset:128
	ds_read_b32 v23, v25
	ds_read_b32 v25, v26 offset:128
	v_add_u32_e32 v26, 8, v17
	v_max_i32_e32 v27, 0, v26
	v_max_i32_e32 v26, 0xffffffe0, v26
	v_lshl_add_u32 v28, v26, 2, v159
	v_add_u32_e32 v26, 9, v17
	v_max_i32_e32 v29, 0, v26
	v_max_i32_e32 v26, 0xffffffe0, v26
	v_lshl_add_u32 v30, v26, 2, v159
	v_add_u32_e32 v26, 10, v17
	v_max_i32_e32 v31, 0, v26
	v_max_i32_e32 v26, 0xffffffe0, v26
	v_lshl_add_u32 v32, v26, 2, v159
	v_add_u32_e32 v26, 11, v17
	v_max_i32_e32 v33, 0, v26
	v_max_i32_e32 v26, 0xffffffe0, v26
	v_lshl_add_u32 v27, v27, 2, v159
	v_lshl_add_u32 v29, v29, 2, v159
	v_lshl_add_u32 v31, v31, 2, v159
	v_lshl_add_u32 v33, v33, 2, v159
	v_lshl_add_u32 v34, v26, 2, v159
	ds_read_b32 v26, v27
	ds_read_b32 v28, v28 offset:128
	ds_read_b32 v27, v29
	ds_read_b32 v29, v30 offset:128
	ds_read_b32 v30, v31
	ds_read_b32 v32, v32 offset:128
	ds_read_b32 v31, v33
	ds_read_b32 v33, v34 offset:128
	v_add_u32_e32 v34, 16, v17
	v_max_i32_e32 v35, 0, v34
	v_max_i32_e32 v34, 0xffffffe0, v34
	v_lshl_add_u32 v36, v34, 2, v159
	v_add_u32_e32 v34, 17, v17
	v_max_i32_e32 v37, 0, v34
	v_max_i32_e32 v34, 0xffffffe0, v34
	v_lshl_add_u32 v38, v34, 2, v159
	v_add_u32_e32 v34, 18, v17
	v_max_i32_e32 v39, 0, v34
	v_max_i32_e32 v34, 0xffffffe0, v34
	v_lshl_add_u32 v40, v34, 2, v159
	v_add_u32_e32 v34, 19, v17
	v_max_i32_e32 v41, 0, v34
	v_max_i32_e32 v34, 0xffffffe0, v34
	v_lshl_add_u32 v35, v35, 2, v159
	v_lshl_add_u32 v37, v37, 2, v159
	v_lshl_add_u32 v39, v39, 2, v159
	v_lshl_add_u32 v41, v41, 2, v159
	v_lshl_add_u32 v42, v34, 2, v159
	ds_read_b32 v34, v35
	ds_read_b32 v36, v36 offset:128
	ds_read_b32 v35, v37
	ds_read_b32 v37, v38 offset:128
	ds_read_b32 v38, v39
	ds_read_b32 v40, v40 offset:128
	ds_read_b32 v39, v41
	ds_read_b32 v41, v42 offset:128
	v_add_u32_e32 v42, 24, v17
	v_max_i32_e32 v43, 0, v42
	v_max_i32_e32 v42, 0xffffffe0, v42
	v_lshl_add_u32 v44, v42, 2, v159
	v_add_u32_e32 v42, 25, v17
	v_max_i32_e32 v45, 0, v42
	v_max_i32_e32 v42, 0xffffffe0, v42
	v_lshl_add_u32 v50, v42, 2, v159
	v_add_u32_e32 v42, 26, v17
	v_max_i32_e32 v46, 0, v42
	v_max_i32_e32 v42, 0xffffffe0, v42
	v_add_u32_e32 v17, 27, v17
	v_lshl_add_u32 v48, v42, 2, v159
	v_max_i32_e32 v42, 0, v17
	v_lshl_add_u32 v43, v43, 2, v159
	v_lshl_add_u32 v45, v45, 2, v159
	v_lshl_add_u32 v46, v46, 2, v159
	v_max_i32_e32 v17, 0xffffffe0, v17
	v_lshl_add_u32 v47, v42, 2, v159
	v_lshl_add_u32 v17, v17, 2, v159
	ds_read_b32 v42, v43
	ds_read_b32 v44, v44 offset:128
	ds_read_b32 v46, v46
	ds_read_b32 v47, v47
	ds_read_b32 v43, v45
	ds_read_b32 v49, v17 offset:128
	ds_read_b32 v48, v48 offset:128
	ds_read_b32 v45, v50 offset:128
	s_waitcnt lgkmcnt(4)
	v_pk_add_f32 v[14:15], v[14:15], v[46:47]
	s_waitcnt lgkmcnt(3)
	v_pk_add_f32 v[12:13], v[12:13], v[42:43]
	v_pk_add_f32 v[10:11], v[10:11], v[38:39]
	v_pk_add_f32 v[8:9], v[8:9], v[34:35]
	v_pk_add_f32 v[6:7], v[6:7], v[30:31]
	v_pk_add_f32 v[4:5], v[4:5], v[26:27]
	v_pk_add_f32 v[2:3], v[2:3], v[22:23]
	v_pk_add_f32 v[0:1], v[0:1], v[18:19]
	s_waitcnt lgkmcnt(1)
	v_pk_add_f32 v[78:79], v[78:79], v[48:49]
	s_waitcnt lgkmcnt(0)
	v_pk_add_f32 v[76:77], v[76:77], v[44:45]
	v_pk_add_f32 v[74:75], v[74:75], v[40:41]
	v_pk_add_f32 v[72:73], v[72:73], v[36:37]
	v_pk_add_f32 v[70:71], v[70:71], v[32:33]
	v_pk_add_f32 v[68:69], v[68:69], v[28:29]
	v_pk_add_f32 v[66:67], v[66:67], v[24:25]
	v_pk_add_f32 v[64:65], v[64:65], v[20:21]

.LBB0_218:
	s_mov_b64 s[2:3], 0
	s_barrier
	s_setprio 0

.LBB0_280:
	s_andn2_b64 vcc, exec, s[2:3]
	s_cbranch_vccnz .LBB0_298
	v_lshl_or_b32 v174, s44, 8, v187
	v_ashrrev_i32_e32 v175, 31, v174
	v_readlane_b32 s2, v243, 6
	v_lshlrev_b64 v[176:177], 1, v[174:175]
	v_readlane_b32 s3, v243, 7
	v_ashrrev_i32_e32 v163, 31, v162
	v_lshlrev_b64 v[198:199], 11, v[162:163]
	v_lshl_add_u64 v[178:179], s[2:3], 0, v[176:177]
	v_lshl_add_u64 v[128:129], v[178:179], 0, v[198:199]
	global_load_dwordx4 v[190:193], v[128:129], off
	global_load_dwordx4 v[194:197], v[128:129], off offset:256
	v_or_b32_e32 v128, 16, v162
	v_ashrrev_i32_e32 v129, 31, v128
	v_lshlrev_b64 v[184:185], 11, v[128:129]
	v_lshl_add_u64 v[128:129], v[178:179], 0, v[184:185]
	global_load_dwordx4 v[148:151], v[128:129], off
	global_load_dwordx4 v[144:147], v[128:129], off offset:256
	v_or_b32_e32 v128, 32, v162
	v_ashrrev_i32_e32 v129, 31, v128
	v_lshlrev_b64 v[182:183], 11, v[128:129]
	v_lshl_add_u64 v[128:129], v[178:179], 0, v[182:183]
	global_load_dwordx4 v[140:143], v[128:129], off
	global_load_dwordx4 v[136:139], v[128:129], off offset:256
	v_or_b32_e32 v128, 48, v162
	v_ashrrev_i32_e32 v129, 31, v128
	v_lshlrev_b64 v[180:181], 11, v[128:129]
	v_lshl_add_u64 v[128:129], v[178:179], 0, v[180:181]
	global_load_dwordx4 v[132:135], v[128:129], off
	s_nop 0
	global_load_dwordx4 v[128:131], v[128:129], off offset:256
	v_lshl_add_u64 v[198:199], s[2:3], 0, v[198:199]
	v_lshl_add_u64 v[176:177], v[198:199], 0, v[176:177]
	v_readlane_b32 s2, v254, 61
	v_readlane_b32 s3, v254, 62
	v_readlane_b32 s26, v254, 18
	v_readlane_b32 s27, v254, 19
	s_waitcnt vmcnt(0)
	v_lshlrev_b32_e32 v200, 16, v190
	v_and_b32_e32 v201, 0xffff0000, v190
	v_lshlrev_b32_e32 v190, 16, v191
	v_and_b32_e32 v191, 0xffff0000, v191
	v_pk_fma_f32 v[204:205], s[54:55], v[126:127], v[190:191]
	v_pk_fma_f32 v[200:201], s[6:7], v[124:125], v[200:201]
	v_lshlrev_b32_e32 v202, 16, v192
	v_and_b32_e32 v203, 0xffff0000, v192
	v_lshlrev_b32_e32 v192, 16, v193
	v_and_b32_e32 v193, 0xffff0000, v193
	v_mul_f32_e32 v161, v201, v201
	v_mul_f32_e32 v168, v205, v205
	v_pk_fma_f32 v[206:207], s[54:55], v[122:123], v[192:193]
	v_pk_fma_f32 v[202:203], s[6:7], v[120:121], v[202:203]
	v_cvt_pk_bf16_f32 v190, v200, v201
	v_fmac_f32_e32 v161, v200, v200
	v_fmac_f32_e32 v168, v204, v204
	v_cvt_pk_bf16_f32 v191, v204, v205
	v_cvt_pk_bf16_f32 v192, v202, v203
	v_cvt_pk_bf16_f32 v193, v206, v207
	global_store_dwordx4 v[176:177], v[190:193], off
	v_add_f32_e32 v161, v161, v168
	v_mul_f32_e32 v168, v203, v203
	v_mul_f32_e32 v190, v207, v207
	v_fmac_f32_e32 v168, v202, v202
	v_fmac_f32_e32 v190, v206, v206
	v_add_f32_e32 v168, v168, v190
	v_lshlrev_b32_e32 v190, 16, v194
	v_and_b32_e32 v191, 0xffff0000, v194
	v_lshlrev_b32_e32 v192, 16, v195
	v_and_b32_e32 v193, 0xffff0000, v195
	v_lshlrev_b32_e32 v194, 16, v196
	v_and_b32_e32 v195, 0xffff0000, v196
	v_lshlrev_b32_e32 v196, 16, v197
	v_and_b32_e32 v197, 0xffff0000, v197
	v_pk_fma_f32 v[198:199], s[54:55], v[118:119], v[192:193]
	v_pk_fma_f32 v[200:201], s[6:7], v[116:117], v[190:191]
	v_add_f32_e32 v161, v161, v168
	v_pk_fma_f32 v[196:197], s[54:55], v[114:115], v[196:197]
	v_pk_fma_f32 v[194:195], s[6:7], v[112:113], v[194:195]
	v_cvt_pk_bf16_f32 v190, v200, v201
	v_cvt_pk_bf16_f32 v191, v198, v199
	v_mul_f32_e32 v168, v201, v201
	v_cvt_pk_bf16_f32 v192, v194, v195
	v_cvt_pk_bf16_f32 v193, v196, v197
	global_store_dwordx4 v[176:177], v[190:193], off offset:256
	v_mul_f32_e32 v176, v199, v199
	v_fmac_f32_e32 v168, v200, v200
	v_fmac_f32_e32 v176, v198, v198
	v_add_f32_e32 v168, v168, v176
	v_mul_f32_e32 v176, v195, v195
	v_mul_f32_e32 v177, v197, v197
	v_fmac_f32_e32 v176, v194, v194
	v_fmac_f32_e32 v177, v196, v196
	v_add_f32_e32 v176, v176, v177
	v_add_f32_e32 v168, v168, v176
	v_add_f32_e32 v168, v161, v168
	v_xor_b32_e32 v161, 16, v233
	v_cmp_lt_i32_e32 vcc, v161, v235
	s_nop 1
	v_cndmask_b32_e32 v161, v233, v161, vcc
	v_lshlrev_b32_e32 v161, 2, v161
	ds_bpermute_b32 v176, v161, v168
	v_cmp_lt_i32_e32 vcc, v234, v235
	s_waitcnt lgkmcnt(0)
	v_add_f32_e32 v190, v168, v176
	v_cndmask_b32_e32 v168, v233, v234, vcc
	v_lshlrev_b32_e32 v168, 2, v168
	ds_bpermute_b32 v191, v168, v190
	v_lshl_add_u64 v[176:177], v[162:163], 3, s[2:3]
	s_and_saveexec_b64 s[2:3], s[26:27]
	s_cbranch_execz .LBB0_283
	s_waitcnt lgkmcnt(0)
	v_add_f32_e32 v190, v190, v191
	v_mul_f32_e32 v190, 0x49800000, v190
	v_trunc_f32_e32 v190, v190
	v_mul_f32_e32 v191, 0x2f800000, v190
	v_floor_f32_e32 v191, v191
	v_fmac_f32_e32 v190, 0xcf800000, v191
	v_cvt_u32_f32_e32 v190, v190
	v_cvt_u32_f32_e32 v191, v191
	v_mov_b64_e32 v[208:209], v[190:191]
.LBB0_283:
	s_or_b64 exec, exec, s[2:3]
	v_lshlrev_b32_e32 v190, 16, v148
	s_waitcnt lgkmcnt(0)
	v_and_b32_e32 v191, 0xffff0000, v148
	v_lshlrev_b32_e32 v148, 16, v149
	v_and_b32_e32 v149, 0xffff0000, v149
	v_pk_fma_f32 v[190:191], s[6:7], v[108:109], v[190:191]
	v_pk_fma_f32 v[194:195], s[54:55], v[110:111], v[148:149]
	v_cvt_pk_bf16_f32 v148, v190, v191
	v_mul_f32_e32 v191, v191, v191
	v_lshlrev_b32_e32 v192, 16, v150
	v_and_b32_e32 v193, 0xffff0000, v150
	v_fmac_f32_e32 v191, v190, v190
	v_mul_f32_e32 v190, v195, v195
	v_lshlrev_b32_e32 v150, 16, v151
	v_and_b32_e32 v151, 0xffff0000, v151
	v_pk_fma_f32 v[192:193], s[6:7], v[104:105], v[192:193]
	v_fmac_f32_e32 v190, v194, v194
	v_pk_fma_f32 v[196:197], s[54:55], v[106:107], v[150:151]
	v_add_f32_e32 v190, v191, v190
	v_mul_f32_e32 v191, v193, v193
	v_cvt_pk_bf16_f32 v149, v194, v195
	v_cvt_pk_bf16_f32 v150, v192, v193
	v_fmac_f32_e32 v191, v192, v192
	v_mul_f32_e32 v192, v197, v197
	v_fmac_f32_e32 v192, v196, v196
	v_add_f32_e32 v191, v191, v192
	v_cvt_pk_bf16_f32 v151, v196, v197
	v_add_f32_e32 v196, v190, v191
	v_lshlrev_b32_e32 v190, 16, v144
	v_and_b32_e32 v191, 0xffff0000, v144
	v_lshlrev_b32_e32 v144, 16, v145
	v_and_b32_e32 v145, 0xffff0000, v145
	v_lshlrev_b32_e32 v192, 16, v146
	v_and_b32_e32 v193, 0xffff0000, v146
	v_lshlrev_b32_e32 v146, 16, v147
	v_and_b32_e32 v147, 0xffff0000, v147
	v_pk_fma_f32 v[194:195], s[54:55], v[102:103], v[144:145]
	v_pk_fma_f32 v[144:145], s[6:7], v[100:101], v[190:191]
	v_pk_fma_f32 v[190:191], s[54:55], v[98:99], v[146:147]
	v_mul_f32_e32 v146, v145, v145
	v_mul_f32_e32 v147, v195, v195
	v_pk_fma_f32 v[192:193], s[6:7], v[96:97], v[192:193]
	v_fmac_f32_e32 v146, v144, v144
	v_fmac_f32_e32 v147, v194, v194
	v_add_f32_e32 v146, v146, v147
	v_mul_f32_e32 v147, v193, v193
	v_mul_f32_e32 v197, v191, v191
	v_fmac_f32_e32 v147, v192, v192
	v_fmac_f32_e32 v197, v190, v190
	v_add_f32_e32 v147, v147, v197
	v_add_f32_e32 v146, v146, v147
	v_add_f32_e32 v196, v196, v146
	ds_bpermute_b32 v197, v161, v196
	v_readlane_b32 s36, v243, 6
	v_readlane_b32 s37, v243, 7
	s_nop 1
	v_lshl_add_u64 v[146:147], s[36:37], 0, v[184:185]
	v_lshl_add_u64 v[184:185], v[174:175], 1, v[146:147]
	global_store_dwordx4 v[184:185], v[148:151], off
	v_cvt_pk_bf16_f32 v146, v144, v145
	s_waitcnt lgkmcnt(0)
	v_add_f32_e32 v144, v196, v197
	ds_bpermute_b32 v145, v168, v144
	v_cvt_pk_bf16_f32 v147, v194, v195
	v_cvt_pk_bf16_f32 v148, v192, v193
	v_cvt_pk_bf16_f32 v149, v190, v191
	global_store_dwordx4 v[184:185], v[146:149], off offset:256
	s_and_saveexec_b64 s[2:3], s[26:27]
	s_cbranch_execz .LBB0_285
	s_waitcnt lgkmcnt(0)
	v_add_f32_e32 v144, v144, v145
	v_mul_f32_e32 v144, 0x49800000, v144
	v_trunc_f32_e32 v144, v144
	v_mul_f32_e32 v145, 0x2f800000, v144
	v_floor_f32_e32 v145, v145
	v_fmac_f32_e32 v144, 0xcf800000, v145
	v_cvt_u32_f32_e32 v144, v144
	v_cvt_u32_f32_e32 v145, v145
	v_mov_b64_e32 v[210:211], v[144:145]
.LBB0_285:
	s_or_b64 exec, exec, s[2:3]
	v_lshlrev_b32_e32 v144, 16, v140
	s_waitcnt lgkmcnt(0)
	v_and_b32_e32 v145, 0xffff0000, v140
	v_lshlrev_b32_e32 v140, 16, v141
	v_and_b32_e32 v141, 0xffff0000, v141
	v_pk_fma_f32 v[144:145], s[6:7], v[92:93], v[144:145]
	v_pk_fma_f32 v[148:149], s[54:55], v[94:95], v[140:141]
	v_cvt_pk_bf16_f32 v140, v144, v145
	v_mul_f32_e32 v145, v145, v145
	v_lshlrev_b32_e32 v146, 16, v142
	v_and_b32_e32 v147, 0xffff0000, v142
	v_fmac_f32_e32 v145, v144, v144
	v_mul_f32_e32 v144, v149, v149
	v_lshlrev_b32_e32 v142, 16, v143
	v_and_b32_e32 v143, 0xffff0000, v143
	v_pk_fma_f32 v[146:147], s[6:7], v[88:89], v[146:147]
	v_fmac_f32_e32 v144, v148, v148
	v_pk_fma_f32 v[150:151], s[54:55], v[90:91], v[142:143]
	v_add_f32_e32 v144, v145, v144
	v_mul_f32_e32 v145, v147, v147
	v_cvt_pk_bf16_f32 v141, v148, v149
	v_cvt_pk_bf16_f32 v142, v146, v147
	v_fmac_f32_e32 v145, v146, v146
	v_mul_f32_e32 v146, v151, v151
	v_fmac_f32_e32 v146, v150, v150
	v_add_f32_e32 v145, v145, v146
	v_cvt_pk_bf16_f32 v143, v150, v151
	v_add_f32_e32 v150, v144, v145
	v_lshlrev_b32_e32 v144, 16, v136
	v_and_b32_e32 v145, 0xffff0000, v136
	v_lshlrev_b32_e32 v136, 16, v137
	v_and_b32_e32 v137, 0xffff0000, v137
	v_lshlrev_b32_e32 v146, 16, v138
	v_and_b32_e32 v147, 0xffff0000, v138
	v_lshlrev_b32_e32 v138, 16, v139
	v_and_b32_e32 v139, 0xffff0000, v139
	v_pk_fma_f32 v[148:149], s[54:55], v[86:87], v[136:137]
	v_pk_fma_f32 v[136:137], s[6:7], v[84:85], v[144:145]
	v_pk_fma_f32 v[144:145], s[54:55], v[82:83], v[138:139]
	v_mul_f32_e32 v138, v137, v137
	v_mul_f32_e32 v139, v149, v149
	v_pk_fma_f32 v[146:147], s[6:7], v[80:81], v[146:147]
	v_fmac_f32_e32 v138, v136, v136
	v_fmac_f32_e32 v139, v148, v148
	v_add_f32_e32 v138, v138, v139
	v_mul_f32_e32 v139, v147, v147
	v_mul_f32_e32 v151, v145, v145
	v_fmac_f32_e32 v139, v146, v146
	v_fmac_f32_e32 v151, v144, v144
	v_add_f32_e32 v139, v139, v151
	v_add_f32_e32 v138, v138, v139
	v_add_f32_e32 v184, v150, v138
	ds_bpermute_b32 v185, v161, v184
	v_lshl_add_u64 v[138:139], s[36:37], 0, v[182:183]
	v_lshl_add_u64 v[150:151], v[174:175], 1, v[138:139]
	global_store_dwordx4 v[150:151], v[140:143], off
	v_cvt_pk_bf16_f32 v138, v136, v137
	s_waitcnt lgkmcnt(0)
	v_add_f32_e32 v136, v184, v185
	ds_bpermute_b32 v137, v168, v136
	v_cvt_pk_bf16_f32 v139, v148, v149
	v_cvt_pk_bf16_f32 v140, v146, v147
	v_cvt_pk_bf16_f32 v141, v144, v145
	global_store_dwordx4 v[150:151], v[138:141], off offset:256
	s_and_saveexec_b64 s[2:3], s[26:27]
	s_cbranch_execz .LBB0_287
	s_waitcnt lgkmcnt(0)
	v_add_f32_e32 v136, v136, v137
	v_mul_f32_e32 v136, 0x49800000, v136
	v_trunc_f32_e32 v136, v136
	v_mul_f32_e32 v137, 0x2f800000, v136
	v_floor_f32_e32 v137, v137
	v_fmac_f32_e32 v136, 0xcf800000, v137
	v_cvt_u32_f32_e32 v136, v136
	v_cvt_u32_f32_e32 v137, v137
	v_mov_b64_e32 v[212:213], v[136:137]
.LBB0_287:
	s_or_b64 exec, exec, s[2:3]
	v_lshlrev_b32_e32 v136, 16, v132
	s_waitcnt lgkmcnt(0)
	v_and_b32_e32 v137, 0xffff0000, v132
	v_lshlrev_b32_e32 v132, 16, v133
	v_and_b32_e32 v133, 0xffff0000, v133
	v_pk_fma_f32 v[136:137], s[6:7], v[76:77], v[136:137]
	v_pk_fma_f32 v[140:141], s[54:55], v[78:79], v[132:133]
	v_cvt_pk_bf16_f32 v132, v136, v137
	v_mul_f32_e32 v137, v137, v137
	v_lshlrev_b32_e32 v138, 16, v134
	v_and_b32_e32 v139, 0xffff0000, v134
	v_fmac_f32_e32 v137, v136, v136
	v_mul_f32_e32 v136, v141, v141
	v_lshlrev_b32_e32 v134, 16, v135
	v_and_b32_e32 v135, 0xffff0000, v135
	v_pk_fma_f32 v[138:139], s[6:7], v[72:73], v[138:139]
	v_fmac_f32_e32 v136, v140, v140
	v_pk_fma_f32 v[142:143], s[54:55], v[74:75], v[134:135]
	v_add_f32_e32 v136, v137, v136
	v_mul_f32_e32 v137, v139, v139
	v_cvt_pk_bf16_f32 v133, v140, v141
	v_cvt_pk_bf16_f32 v134, v138, v139
	v_fmac_f32_e32 v137, v138, v138
	v_mul_f32_e32 v138, v143, v143
	v_fmac_f32_e32 v138, v142, v142
	v_add_f32_e32 v137, v137, v138
	v_cvt_pk_bf16_f32 v135, v142, v143
	v_add_f32_e32 v142, v136, v137
	v_lshlrev_b32_e32 v136, 16, v128
	v_and_b32_e32 v137, 0xffff0000, v128
	v_lshlrev_b32_e32 v128, 16, v129
	v_and_b32_e32 v129, 0xffff0000, v129
	v_lshlrev_b32_e32 v138, 16, v130
	v_and_b32_e32 v139, 0xffff0000, v130
	v_lshlrev_b32_e32 v130, 16, v131
	v_and_b32_e32 v131, 0xffff0000, v131
	v_pk_fma_f32 v[140:141], s[54:55], v[70:71], v[128:129]
	v_pk_fma_f32 v[128:129], s[6:7], v[68:69], v[136:137]
	v_pk_fma_f32 v[136:137], s[54:55], v[66:67], v[130:131]
	v_mul_f32_e32 v130, v129, v129
	v_mul_f32_e32 v131, v141, v141
	v_pk_fma_f32 v[138:139], s[6:7], v[64:65], v[138:139]
	v_fmac_f32_e32 v130, v128, v128
	v_fmac_f32_e32 v131, v140, v140
	v_add_f32_e32 v130, v130, v131
	v_mul_f32_e32 v131, v139, v139
	v_mul_f32_e32 v143, v137, v137
	v_fmac_f32_e32 v131, v138, v138
	v_fmac_f32_e32 v143, v136, v136
	v_add_f32_e32 v131, v131, v143
	v_add_f32_e32 v130, v130, v131
	v_add_f32_e32 v144, v142, v130
	ds_bpermute_b32 v145, v161, v144
	v_lshl_add_u64 v[130:131], s[36:37], 0, v[180:181]
	v_lshl_add_u64 v[142:143], v[174:175], 1, v[130:131]
	global_store_dwordx4 v[142:143], v[132:135], off
	v_cvt_pk_bf16_f32 v130, v128, v129
	s_waitcnt lgkmcnt(0)
	v_add_f32_e32 v128, v144, v145
	ds_bpermute_b32 v129, v168, v128
	v_cvt_pk_bf16_f32 v131, v140, v141
	v_cvt_pk_bf16_f32 v132, v138, v139
	v_cvt_pk_bf16_f32 v133, v136, v137
	global_store_dwordx4 v[142:143], v[130:133], off offset:256
	s_and_saveexec_b64 s[2:3], s[26:27]
	s_cbranch_execz .LBB0_289
	s_waitcnt lgkmcnt(0)
	v_add_f32_e32 v128, v128, v129
	v_mul_f32_e32 v128, 0x49800000, v128
	v_trunc_f32_e32 v128, v128
	v_mul_f32_e32 v129, 0x2f800000, v128
	v_floor_f32_e32 v129, v129
	v_fmac_f32_e32 v128, 0xcf800000, v129
	v_cvt_u32_f32_e32 v128, v128
	v_cvt_u32_f32_e32 v129, v129
	v_mov_b64_e32 v[214:215], v[128:129]
.LBB0_289:
	s_or_b64 exec, exec, s[2:3]
	s_waitcnt lgkmcnt(0)
	v_lshlrev_b64 v[128:129], 11, v[162:163]
	s_mov_b64 s[2:3], 0x40000
	v_lshl_add_u64 v[198:199], v[128:129], 0, s[2:3]
	v_lshl_add_u64 v[130:131], v[178:179], 0, v[198:199]
	global_load_dwordx4 v[190:193], v[130:131], off
	global_load_dwordx4 v[194:197], v[130:131], off offset:256
	s_mov_b64 s[2:3], 0x48000
	v_lshl_add_u64 v[184:185], v[128:129], 0, s[2:3]
	s_mov_b64 s[2:3], 0x50000
	v_lshl_add_u64 v[182:183], v[128:129], 0, s[2:3]
	s_mov_b64 s[2:3], 0x58000
	v_lshl_add_u64 v[130:131], v[178:179], 0, v[184:185]
	v_lshl_add_u64 v[180:181], v[128:129], 0, s[2:3]
	global_load_dwordx4 v[148:151], v[130:131], off
	global_load_dwordx4 v[144:147], v[130:131], off offset:256
	v_lshl_add_u64 v[130:131], v[178:179], 0, v[182:183]
	v_lshl_add_u64 v[128:129], v[178:179], 0, v[180:181]
	global_load_dwordx4 v[140:143], v[130:131], off
	global_load_dwordx4 v[136:139], v[130:131], off offset:256
	global_load_dwordx4 v[132:135], v[128:129], off
	s_nop 0
	global_load_dwordx4 v[128:131], v[128:129], off offset:256
	s_and_saveexec_b64 s[100:101], s[26:27]
	global_atomic_add_x2 v[176:177], v[208:209], off
	global_atomic_add_x2 v[176:177], v[210:211], off offset:128
	global_atomic_add_x2 v[176:177], v[212:213], off offset:256
	global_atomic_add_x2 v[176:177], v[214:215], off offset:384
	s_mov_b64 exec, s[100:101]
	v_lshl_add_u64 v[198:199], s[36:37], 0, v[198:199]
	v_lshl_add_u64 v[198:199], v[174:175], 1, v[198:199]
	s_waitcnt vmcnt(11)
	v_lshlrev_b32_e32 v178, 16, v190
	v_and_b32_e32 v179, 0xffff0000, v190
	v_lshlrev_b32_e32 v190, 16, v191
	v_and_b32_e32 v191, 0xffff0000, v191
	v_pk_fma_f32 v[178:179], s[6:7], v[60:61], v[178:179]
	v_pk_fma_f32 v[202:203], s[54:55], v[62:63], v[190:191]
	v_mul_f32_e32 v163, v179, v179
	v_lshlrev_b32_e32 v200, 16, v192
	v_and_b32_e32 v201, 0xffff0000, v192
	v_lshlrev_b32_e32 v192, 16, v193
	v_and_b32_e32 v193, 0xffff0000, v193
	v_cvt_pk_bf16_f32 v190, v178, v179
	v_fmac_f32_e32 v163, v178, v178
	v_mul_f32_e32 v178, v203, v203
	v_pk_fma_f32 v[204:205], s[54:55], v[58:59], v[192:193]
	v_pk_fma_f32 v[200:201], s[6:7], v[56:57], v[200:201]
	v_fmac_f32_e32 v178, v202, v202
	v_add_f32_e32 v163, v163, v178
	v_mul_f32_e32 v178, v201, v201
	v_mul_f32_e32 v179, v205, v205
	v_fmac_f32_e32 v178, v200, v200
	v_fmac_f32_e32 v179, v204, v204
	v_add_f32_e32 v178, v178, v179
	v_cvt_pk_bf16_f32 v191, v202, v203
	v_add_f32_e32 v163, v163, v178
	s_waitcnt vmcnt(10)
	v_lshlrev_b32_e32 v178, 16, v194
	v_and_b32_e32 v179, 0xffff0000, v194
	v_cvt_pk_bf16_f32 v192, v200, v201
	v_cvt_pk_bf16_f32 v193, v204, v205
	global_store_dwordx4 v[198:199], v[190:193], off
	v_pk_fma_f32 v[178:179], s[6:7], v[52:53], v[178:179]
	v_lshlrev_b32_e32 v194, 16, v197
	v_lshlrev_b32_e32 v190, 16, v195
	v_and_b32_e32 v191, 0xffff0000, v195
	v_lshlrev_b32_e32 v192, 16, v196
	v_and_b32_e32 v193, 0xffff0000, v196
	v_and_b32_e32 v195, 0xffff0000, v197
	v_pk_fma_f32 v[196:197], s[54:55], v[54:55], v[190:191]
	v_cvt_pk_bf16_f32 v190, v178, v179
	v_mul_f32_e32 v179, v179, v179
	v_fmac_f32_e32 v179, v178, v178
	v_mul_f32_e32 v178, v197, v197
	v_pk_fma_f32 v[194:195], s[54:55], v[50:51], v[194:195]
	v_pk_fma_f32 v[200:201], s[6:7], v[48:49], v[192:193]
	v_fmac_f32_e32 v178, v196, v196
	v_cvt_pk_bf16_f32 v191, v196, v197
	v_cvt_pk_bf16_f32 v192, v200, v201
	v_cvt_pk_bf16_f32 v193, v194, v195
	global_store_dwordx4 v[198:199], v[190:193], off offset:256
	v_add_f32_e32 v178, v179, v178
	v_mul_f32_e32 v179, v201, v201
	v_mul_f32_e32 v190, v195, v195
	v_fmac_f32_e32 v179, v200, v200
	v_fmac_f32_e32 v190, v194, v194
	v_add_f32_e32 v179, v179, v190
	v_add_f32_e32 v178, v178, v179
	v_add_f32_e32 v163, v163, v178
	ds_bpermute_b32 v178, v161, v163
	s_waitcnt lgkmcnt(0)
	v_add_f32_e32 v163, v163, v178
	ds_bpermute_b32 v178, v168, v163
	s_and_saveexec_b64 s[2:3], s[26:27]
	s_cbranch_execz .LBB0_291
	s_waitcnt lgkmcnt(0)
	v_add_f32_e32 v163, v163, v178
	v_mul_f32_e32 v163, 0x49800000, v163
	v_trunc_f32_e32 v163, v163
	v_mul_f32_e32 v178, 0x2f800000, v163
	v_floor_f32_e32 v179, v178
	v_fmac_f32_e32 v163, 0xcf800000, v179
	v_cvt_u32_f32_e32 v178, v163
	v_cvt_u32_f32_e32 v179, v179
	global_atomic_add_x2 v[176:177], v[178:179], off offset:1024
.LBB0_291:
	s_or_b64 exec, exec, s[2:3]
	s_waitcnt vmcnt(11) lgkmcnt(0)
	v_lshlrev_b32_e32 v178, 16, v148
	v_and_b32_e32 v179, 0xffff0000, v148
	v_lshlrev_b32_e32 v148, 16, v149
	v_and_b32_e32 v149, 0xffff0000, v149
	v_pk_fma_f32 v[178:179], s[6:7], v[44:45], v[178:179]
	v_pk_fma_f32 v[192:193], s[54:55], v[46:47], v[148:149]
	v_mul_f32_e32 v163, v179, v179
	v_lshlrev_b32_e32 v190, 16, v150
	v_and_b32_e32 v191, 0xffff0000, v150
	v_lshlrev_b32_e32 v150, 16, v151
	v_and_b32_e32 v151, 0xffff0000, v151
	v_cvt_pk_bf16_f32 v148, v178, v179
	v_fmac_f32_e32 v163, v178, v178
	v_mul_f32_e32 v178, v193, v193
	v_pk_fma_f32 v[194:195], s[54:55], v[42:43], v[150:151]
	v_pk_fma_f32 v[190:191], s[6:7], v[40:41], v[190:191]
	v_fmac_f32_e32 v178, v192, v192
	v_add_f32_e32 v163, v163, v178
	v_mul_f32_e32 v178, v191, v191
	v_mul_f32_e32 v179, v195, v195
	v_fmac_f32_e32 v178, v190, v190
	v_fmac_f32_e32 v179, v194, v194
	v_add_f32_e32 v178, v178, v179
	v_add_f32_e32 v163, v163, v178
	s_waitcnt vmcnt(10)
	v_lshlrev_b32_e32 v178, 16, v144
	v_and_b32_e32 v179, 0xffff0000, v144
	v_lshlrev_b32_e32 v144, 16, v145
	v_and_b32_e32 v145, 0xffff0000, v145
	v_cvt_pk_bf16_f32 v149, v192, v193
	v_cvt_pk_bf16_f32 v150, v190, v191
	v_lshlrev_b32_e32 v190, 16, v146
	v_and_b32_e32 v191, 0xffff0000, v146
	v_lshlrev_b32_e32 v146, 16, v147
	v_and_b32_e32 v147, 0xffff0000, v147
	v_pk_fma_f32 v[192:193], s[54:55], v[38:39], v[144:145]
	v_pk_fma_f32 v[144:145], s[6:7], v[36:37], v[178:179]
	v_pk_fma_f32 v[178:179], s[54:55], v[34:35], v[146:147]
	v_mul_f32_e32 v146, v145, v145
	v_mul_f32_e32 v147, v193, v193
	v_pk_fma_f32 v[190:191], s[6:7], v[32:33], v[190:191]
	v_fmac_f32_e32 v146, v144, v144
	v_fmac_f32_e32 v147, v192, v192
	v_cvt_pk_bf16_f32 v151, v194, v195
	v_add_f32_e32 v146, v146, v147
	v_mul_f32_e32 v147, v191, v191
	v_mul_f32_e32 v194, v179, v179
	v_fmac_f32_e32 v147, v190, v190
	v_fmac_f32_e32 v194, v178, v178
	v_add_f32_e32 v147, v147, v194
	v_add_f32_e32 v146, v146, v147
	v_add_f32_e32 v163, v163, v146
	ds_bpermute_b32 v194, v161, v163
	v_lshl_add_u64 v[146:147], s[36:37], 0, v[184:185]
	v_lshl_add_u64 v[184:185], v[174:175], 1, v[146:147]
	global_store_dwordx4 v[184:185], v[148:151], off
	v_cvt_pk_bf16_f32 v146, v144, v145
	s_waitcnt lgkmcnt(0)
	v_add_f32_e32 v144, v163, v194
	ds_bpermute_b32 v145, v168, v144
	v_cvt_pk_bf16_f32 v147, v192, v193
	v_cvt_pk_bf16_f32 v148, v190, v191
	v_cvt_pk_bf16_f32 v149, v178, v179
	global_store_dwordx4 v[184:185], v[146:149], off offset:256
	s_and_saveexec_b64 s[2:3], s[26:27]
	s_cbranch_execz .LBB0_293
	s_waitcnt lgkmcnt(0)
	v_add_f32_e32 v144, v144, v145
	v_mul_f32_e32 v144, 0x49800000, v144
	v_trunc_f32_e32 v144, v144
	v_mul_f32_e32 v145, 0x2f800000, v144
	v_floor_f32_e32 v145, v145
	v_fmac_f32_e32 v144, 0xcf800000, v145
	v_cvt_u32_f32_e32 v144, v144
	v_cvt_u32_f32_e32 v145, v145
	global_atomic_add_x2 v[176:177], v[144:145], off offset:1152
.LBB0_293:
	s_or_b64 exec, exec, s[2:3]
	s_waitcnt vmcnt(11)
	v_lshlrev_b32_e32 v144, 16, v140
	s_waitcnt lgkmcnt(0)
	v_and_b32_e32 v145, 0xffff0000, v140
	v_lshlrev_b32_e32 v140, 16, v141
	v_and_b32_e32 v141, 0xffff0000, v141
	v_pk_fma_f32 v[144:145], s[6:7], v[28:29], v[144:145]
	v_pk_fma_f32 v[148:149], s[54:55], v[30:31], v[140:141]
	v_cvt_pk_bf16_f32 v140, v144, v145
	v_mul_f32_e32 v145, v145, v145
	v_lshlrev_b32_e32 v146, 16, v142
	v_and_b32_e32 v147, 0xffff0000, v142
	v_fmac_f32_e32 v145, v144, v144
	v_mul_f32_e32 v144, v149, v149
	v_lshlrev_b32_e32 v142, 16, v143
	v_and_b32_e32 v143, 0xffff0000, v143
	v_pk_fma_f32 v[146:147], s[6:7], v[24:25], v[146:147]
	v_fmac_f32_e32 v144, v148, v148
	v_pk_fma_f32 v[150:151], s[54:55], v[26:27], v[142:143]
	v_add_f32_e32 v144, v145, v144
	v_mul_f32_e32 v145, v147, v147
	v_cvt_pk_bf16_f32 v141, v148, v149
	v_cvt_pk_bf16_f32 v142, v146, v147
	v_fmac_f32_e32 v145, v146, v146
	v_mul_f32_e32 v146, v151, v151
	v_fmac_f32_e32 v146, v150, v150
	v_add_f32_e32 v145, v145, v146
	v_cvt_pk_bf16_f32 v143, v150, v151
	v_add_f32_e32 v150, v144, v145
	s_waitcnt vmcnt(10)
	v_lshlrev_b32_e32 v144, 16, v136
	v_and_b32_e32 v145, 0xffff0000, v136
	v_lshlrev_b32_e32 v136, 16, v137
	v_and_b32_e32 v137, 0xffff0000, v137
	v_lshlrev_b32_e32 v146, 16, v138
	v_and_b32_e32 v147, 0xffff0000, v138
	v_lshlrev_b32_e32 v138, 16, v139
	v_and_b32_e32 v139, 0xffff0000, v139
	v_pk_fma_f32 v[148:149], s[54:55], v[22:23], v[136:137]
	v_pk_fma_f32 v[136:137], s[6:7], v[20:21], v[144:145]
	v_pk_fma_f32 v[144:145], s[54:55], v[18:19], v[138:139]
	v_mul_f32_e32 v138, v137, v137
	v_mul_f32_e32 v139, v149, v149
	v_pk_fma_f32 v[146:147], s[6:7], v[16:17], v[146:147]
	v_fmac_f32_e32 v138, v136, v136
	v_fmac_f32_e32 v139, v148, v148
	v_add_f32_e32 v138, v138, v139
	v_mul_f32_e32 v139, v147, v147
	v_mul_f32_e32 v151, v145, v145
	v_fmac_f32_e32 v139, v146, v146
	v_fmac_f32_e32 v151, v144, v144
	v_add_f32_e32 v139, v139, v151
	v_add_f32_e32 v138, v138, v139
	v_add_f32_e32 v163, v150, v138
	ds_bpermute_b32 v178, v161, v163
	v_lshl_add_u64 v[138:139], s[36:37], 0, v[182:183]
	v_lshl_add_u64 v[150:151], v[174:175], 1, v[138:139]
	global_store_dwordx4 v[150:151], v[140:143], off
	v_cvt_pk_bf16_f32 v138, v136, v137
	s_waitcnt lgkmcnt(0)
	v_add_f32_e32 v136, v163, v178
	ds_bpermute_b32 v137, v168, v136
	v_cvt_pk_bf16_f32 v139, v148, v149
	v_cvt_pk_bf16_f32 v140, v146, v147
	v_cvt_pk_bf16_f32 v141, v144, v145
	global_store_dwordx4 v[150:151], v[138:141], off offset:256
	s_and_saveexec_b64 s[2:3], s[26:27]
	s_cbranch_execz .LBB0_295
	s_waitcnt lgkmcnt(0)
	v_add_f32_e32 v136, v136, v137
	v_mul_f32_e32 v136, 0x49800000, v136
	v_trunc_f32_e32 v136, v136
	v_mul_f32_e32 v137, 0x2f800000, v136
	v_floor_f32_e32 v137, v137
	v_fmac_f32_e32 v136, 0xcf800000, v137
	v_cvt_u32_f32_e32 v136, v136
	v_cvt_u32_f32_e32 v137, v137
	global_atomic_add_x2 v[176:177], v[136:137], off offset:1280
.LBB0_295:
	s_or_b64 exec, exec, s[2:3]
	s_waitcnt vmcnt(11)
	v_lshlrev_b32_e32 v136, 16, v132
	s_waitcnt lgkmcnt(0)
	v_and_b32_e32 v137, 0xffff0000, v132
	v_lshlrev_b32_e32 v132, 16, v133
	v_and_b32_e32 v133, 0xffff0000, v133
	v_pk_fma_f32 v[136:137], s[6:7], v[12:13], v[136:137]
	v_pk_fma_f32 v[140:141], s[54:55], v[14:15], v[132:133]
	v_cvt_pk_bf16_f32 v132, v136, v137
	v_mul_f32_e32 v137, v137, v137
	v_lshlrev_b32_e32 v138, 16, v134
	v_and_b32_e32 v139, 0xffff0000, v134
	v_fmac_f32_e32 v137, v136, v136
	v_mul_f32_e32 v136, v141, v141
	v_lshlrev_b32_e32 v134, 16, v135
	v_and_b32_e32 v135, 0xffff0000, v135
	v_pk_fma_f32 v[138:139], s[6:7], v[8:9], v[138:139]
	v_fmac_f32_e32 v136, v140, v140
	v_pk_fma_f32 v[142:143], s[54:55], v[10:11], v[134:135]
	v_add_f32_e32 v136, v137, v136
	v_mul_f32_e32 v137, v139, v139
	v_cvt_pk_bf16_f32 v133, v140, v141
	v_cvt_pk_bf16_f32 v134, v138, v139
	v_fmac_f32_e32 v137, v138, v138
	v_mul_f32_e32 v138, v143, v143
	v_fmac_f32_e32 v138, v142, v142
	v_add_f32_e32 v137, v137, v138
	v_cvt_pk_bf16_f32 v135, v142, v143
	v_add_f32_e32 v142, v136, v137
	s_waitcnt vmcnt(10)
	v_lshlrev_b32_e32 v136, 16, v128
	v_and_b32_e32 v137, 0xffff0000, v128
	v_lshlrev_b32_e32 v128, 16, v129
	v_and_b32_e32 v129, 0xffff0000, v129
	v_lshlrev_b32_e32 v138, 16, v130
	v_and_b32_e32 v139, 0xffff0000, v130
	v_lshlrev_b32_e32 v130, 16, v131
	v_and_b32_e32 v131, 0xffff0000, v131
	v_pk_fma_f32 v[140:141], s[54:55], v[6:7], v[128:129]
	v_pk_fma_f32 v[128:129], s[6:7], v[4:5], v[136:137]
	v_pk_fma_f32 v[136:137], s[54:55], v[2:3], v[130:131]
	v_mul_f32_e32 v130, v129, v129
	v_mul_f32_e32 v131, v141, v141
	v_pk_fma_f32 v[138:139], s[6:7], v[0:1], v[138:139]
	v_fmac_f32_e32 v130, v128, v128
	v_fmac_f32_e32 v131, v140, v140
	v_add_f32_e32 v130, v130, v131
	v_mul_f32_e32 v131, v139, v139
	v_mul_f32_e32 v143, v137, v137
	v_fmac_f32_e32 v131, v138, v138
	v_fmac_f32_e32 v143, v136, v136
	v_add_f32_e32 v131, v131, v143
	v_add_f32_e32 v130, v130, v131
	v_add_f32_e32 v144, v142, v130
	ds_bpermute_b32 v145, v161, v144
	v_lshl_add_u64 v[130:131], s[36:37], 0, v[180:181]
	v_lshl_add_u64 v[142:143], v[174:175], 1, v[130:131]
	global_store_dwordx4 v[142:143], v[132:135], off
	v_cvt_pk_bf16_f32 v130, v128, v129
	s_waitcnt lgkmcnt(0)
	v_add_f32_e32 v128, v144, v145
	ds_bpermute_b32 v129, v168, v128
	v_cvt_pk_bf16_f32 v131, v140, v141
	v_cvt_pk_bf16_f32 v132, v138, v139
	v_cvt_pk_bf16_f32 v133, v136, v137
	global_store_dwordx4 v[142:143], v[130:133], off offset:256
	s_and_saveexec_b64 s[2:3], s[26:27]
	s_cbranch_execz .LBB0_297
	s_waitcnt lgkmcnt(0)
	v_add_f32_e32 v128, v128, v129
	v_mul_f32_e32 v128, 0x49800000, v128
	v_trunc_f32_e32 v128, v128
	v_mul_f32_e32 v129, 0x2f800000, v128
	v_floor_f32_e32 v129, v129
	v_fmac_f32_e32 v128, 0xcf800000, v129
	v_cvt_u32_f32_e32 v128, v128
	v_cvt_u32_f32_e32 v129, v129
	global_atomic_add_x2 v[176:177], v[128:129], off offset:1408

	.amdhsa_kernel _Z8mega_fwd4Args
		.amdhsa_group_segment_fixed_size 0
		.amdhsa_private_segment_fixed_size 0
		.amdhsa_kernarg_size 376
		.amdhsa_user_sgpr_count 2
		.amdhsa_user_sgpr_dispatch_ptr 0
		.amdhsa_user_sgpr_queue_ptr 0
		.amdhsa_user_sgpr_kernarg_segment_ptr 1
		.amdhsa_user_sgpr_dispatch_id 0
		.amdhsa_user_sgpr_kernarg_preload_length 0
		.amdhsa_user_sgpr_kernarg_preload_offset 0
		.amdhsa_user_sgpr_private_segment_size 0
		.amdhsa_uses_dynamic_stack 0
		.amdhsa_enable_private_segment 0
		.amdhsa_system_sgpr_workgroup_id_x 1
		.amdhsa_system_sgpr_workgroup_id_y 0
		.amdhsa_system_sgpr_workgroup_id_z 0
		.amdhsa_system_sgpr_workgroup_info 0
		.amdhsa_system_vgpr_workitem_id 2
		.amdhsa_next_free_vgpr 255
		.amdhsa_next_free_sgpr 102
		.amdhsa_accum_offset 256
		.amdhsa_reserve_vcc 1
		.amdhsa_float_round_mode_32 0
		.amdhsa_float_round_mode_16_64 0
		.amdhsa_float_denorm_mode_32 3
		.amdhsa_float_denorm_mode_16_64 3
		.amdhsa_dx10_clamp 1
		.amdhsa_ieee_mode 1
		.amdhsa_fp16_overflow 0
		.amdhsa_tg_split 0
		.amdhsa_exception_fp_ieee_invalid_op 0
		.amdhsa_exception_fp_denorm_src 0
		.amdhsa_exception_fp_ieee_div_zero 0
		.amdhsa_exception_fp_ieee_overflow 0
		.amdhsa_exception_fp_ieee_underflow 0
		.amdhsa_exception_fp_ieee_inexact 0
		.amdhsa_exception_int_div_zero 0
	.end_amdhsa_kernel

amdhsa.kernels:
  - .agpr_count:     0
    .args:
      - .offset:         0
        .size:           120
        .value_kind:     by_value
      - .offset:         120
        .size:           4
        .value_kind:     hidden_block_count_x
      - .offset:         124
        .size:           4
        .value_kind:     hidden_block_count_y
      - .offset:         128
        .size:           4
        .value_kind:     hidden_block_count_z
      - .offset:         132
        .size:           2
        .value_kind:     hidden_group_size_x
      - .offset:         134
        .size:           2
        .value_kind:     hidden_group_size_y
      - .offset:         136
        .size:           2
        .value_kind:     hidden_group_size_z
      - .offset:         138
        .size:           2
        .value_kind:     hidden_remainder_x
      - .offset:         140
        .size:           2
        .value_kind:     hidden_remainder_y
      - .offset:         142
        .size:           2
        .value_kind:     hidden_remainder_z
      - .offset:         160
        .size:           8
        .value_kind:     hidden_global_offset_x
      - .offset:         168
        .size:           8
        .value_kind:     hidden_global_offset_y
      - .offset:         176
        .size:           8
        .value_kind:     hidden_global_offset_z
      - .offset:         184
        .size:           2
        .value_kind:     hidden_grid_dims
      - .offset:         208
        .size:           8
        .value_kind:     hidden_multigrid_sync_arg
      - .offset:         240
        .size:           4
        .value_kind:     hidden_dynamic_lds_size
    .group_segment_fixed_size: 0
    .kernarg_segment_align: 8
    .kernarg_segment_size: 376
    .language:       OpenCL C
    .language_version:
      - 2
      - 0
    .max_flat_workgroup_size: 512
    .name:           _Z8mega_fwd4Args
    .private_segment_fixed_size: 0
    .sgpr_count:     108
    .sgpr_spill_count: 237
    .symbol:         _Z8mega_fwd4Args.kd
    .uniform_work_group_size: 1
    .uses_dynamic_stack: false
    .vgpr_count:     255
    .vgpr_spill_count: 0
    .wavefront_size: 64
